# split grid barriers (normM->w_in, post->q as group barriers + arrive/late-wait counters) + final norm takes group-local rows behind a group barrier
# speedup vs baseline: 1.0100x; 1.0037x over previous
.LBB0_442:
	v_readlane_b32 s4, v255, 15
	s_add_i32 s34, s4, 3
	v_readlane_b32 s4, v255, 0
	v_readlane_b32 s5, v255, 1
	s_cmp_ge_i32 s34, s5
	s_cbranch_scc1 .LBB0_496
	s_bitcmp0_b32 s32, 0
	s_cbranch_scc1 .Lgb2_slow
	s_waitcnt vmcnt(0)
	s_barrier
	s_add_i32 s32, s32, 16
	v_cmp_eq_u32_e32 vcc, 0, v0
	s_and_saveexec_b64 s[4:5], vcc
	s_cbranch_execz .Lgb2_join
	s_load_dwordx2 s[8:9], s[0:1], 0xd8
	s_and_b32 s11, s87, 63
	s_lshl_b32 s11, s11, 8
	v_mov_b32_e32 v248, 0
	v_mov_b32_e32 v249, 1
	s_mov_b32 s10, 0
	s_waitcnt lgkmcnt(0)
	s_add_u32 s8, s8, 0x10000
	s_addc_u32 s9, s9, 0
	s_bitcmp1_b32 s34, 0
	s_cbranch_scc1 .Lgb2_noarr
	global_atomic_add v248, v249, s[8:9] offset:128

.LBB0_1272:
	v_readlane_b32 s4, v255, 0
	v_readlane_b32 s6, v255, 15
	v_readlane_b32 s5, v255, 1
	s_cmp_ge_i32 s6, s4
	s_cselect_b64 s[2:3], -1, 0
	s_cmp_lt_i32 s6, s5
	s_cselect_b64 s[4:5], -1, 0
	s_and_b64 s[2:3], s[2:3], s[4:5]
	s_and_b64 vcc, exec, s[2:3]
	s_cbranch_vccz .LBB0_1332
	v_readlane_b32 s6, v255, 4
	v_ashrrev_i32_e32 v1, 6, v0
	s_movk_i32 s12, 0x4000
	v_add_u32_e32 v32, s6, v1
	s_cmp_lg_u32 s65, 0x100
	s_cbranch_scc1 .Lfin_std
	v_readlane_b32 s6, v255, 7
	v_lshlrev_b32_e32 v1, 3, v1
	v_add_u32_e32 v32, s6, v1
	s_mov_b32 s38, 1
	s_mov_b32 s39, 0
	v_readfirstlane_b32 s12, v32
	s_add_i32 s12, s12, 8
.Lfin_std:
	s_mov_b64 s[2:3], s[0:1]
	s_mov_b64 s[4:5], s[0:1]
	v_cmp_gt_i32_e32 vcc, s12, v32
	s_and_saveexec_b64 s[6:7], vcc
	s_cbranch_execz .LBB0_1278
	s_load_dwordx2 s[4:5], s[4:5], 0xc8
	s_waitcnt vmcnt(0)
	v_and_b32_e32 v36, 63, v0
	s_load_dwordx2 s[2:3], s[2:3], 0xd8
	v_lshlrev_b32_e32 v24, 4, v36
	v_or_b32_e32 v25, 0x1000, v24
	v_or_b32_e32 v26, 0x1400, v24
	v_or_b32_e32 v33, 0x1800, v24
	s_waitcnt lgkmcnt(0)
	global_load_dwordx4 v[0:3], v24, s[4:5]
	global_load_dwordx4 v[4:7], v24, s[4:5] offset:1024
	global_load_dwordx4 v[8:11], v24, s[4:5] offset:2048
	global_load_dwordx4 v[12:15], v24, s[4:5] offset:3072
	global_load_dwordx4 v[16:19], v25, s[4:5]
	global_load_dwordx4 v[20:23], v26, s[4:5]
	v_or_b32_e32 v40, 0x1c00, v24
	global_load_dwordx4 v[24:27], v33, s[4:5]
	global_load_dwordx4 v[28:31], v40, s[4:5]
	v_ashrrev_i32_e32 v33, 31, v32
	v_lshlrev_b64 v[34:35], 12, v[32:33]
	v_lshl_add_u64 v[34:35], s[2:3], 0, v[34:35]
	v_lshlrev_b32_e32 v36, 3, v36
	v_mov_b32_e32 v37, 0
	v_lshl_add_u64 v[34:35], v[34:35], 0, v[36:37]
	s_mov_b64 s[4:5], 0x13d00000
	s_mov_b32 s8, 0x13d00000
	v_lshl_add_u64 v[38:39], v[34:35], 0, s[4:5]
	v_add_co_u32_e32 v34, vcc, s8, v34
	s_lshl_b64 s[8:9], s[38:39], 13
	s_nop 0
	v_addc_co_u32_e32 v35, vcc, 0, v35, vcc
	global_load_dwordx2 v[66:67], v[38:39], off offset:512
	global_load_dwordx2 v[64:65], v[38:39], off offset:1024
	global_load_dwordx2 v[62:63], v[38:39], off offset:1536
	global_load_dwordx2 v[60:61], v[38:39], off offset:2048
	global_load_dwordx2 v[68:69], v[34:35], off
	global_load_dwordx2 v[58:59], v[38:39], off offset:2560
	global_load_dwordx2 v[56:57], v[38:39], off offset:3072
	global_load_dwordx2 v[54:55], v[38:39], off offset:3584
	v_add_u32_e32 v38, s38, v32
	v_ashrrev_i32_e32 v39, 31, v38
	v_lshlrev_b64 v[38:39], 12, v[38:39]
	v_or_b32_e32 v38, v38, v36
	v_lshlrev_b64 v[34:35], 13, v[32:33]
	v_lshl_add_u64 v[36:37], s[2:3], 0, v[38:39]
	v_or_b32_e32 v34, v40, v34
	v_lshl_add_u64 v[36:37], v[36:37], 0, s[4:5]
	s_lshl_b64 s[10:11], s[38:39], 12
	s_mov_b64 s[14:15], 0
	s_add_i32 s13, s12, -1
	v_mov_b32_e32 v33, 0x358637bd
	s_mov_b32 s16, 0xf800000
	v_mov_b32_e32 v70, 0x260
	s_movk_i32 s17, 0xf000
	s_branch .LBB0_1276
